# attention epilogue: norm-weight loads waited for at their first consumer (after the LDS reduction and rsqrt/divide) instead of right after issue
# baseline (speedup 1.0000x reference)
.LBB0_1570:
	s_or_b64 exec, exec, s[2:3]
	s_waitcnt lgkmcnt(0)
	s_barrier
	s_load_dwordx2 s[2:3], s[0:1], 0x48
	s_lshl_b64 s[6:7], s[6:7], 2
	v_lshlrev_b32_e32 v2, 2, v165
	v_lshl_add_u32 v100, v172, 2, 0
	v_add_u32_e32 v90, 0x2000, v100
	s_waitcnt lgkmcnt(0)
	s_add_u32 s2, s2, s6
	s_addc_u32 s3, s3, s7
	global_load_dwordx4 v[30:33], v2, s[2:3]
	global_load_dwordx4 v[26:29], v2, s[2:3] offset:32
	global_load_dwordx4 v[22:25], v2, s[2:3] offset:64
	global_load_dwordx4 v[18:21], v2, s[2:3] offset:96
	global_load_dwordx4 v[14:17], v2, s[2:3] offset:128
	global_load_dwordx4 v[10:13], v2, s[2:3] offset:160
	global_load_dwordx4 v[6:9], v2, s[2:3] offset:192
	s_nop 0
	global_load_dwordx4 v[2:5], v2, s[2:3] offset:224
	s_add_u32 s2, s23, s4
	s_addc_u32 s3, s24, s5
	v_lshlrev_b64 v[114:115], 11, v[0:1]
	v_lshl_add_u64 v[114:115], s[2:3], 0, v[114:115]
	v_lshlrev_b32_e32 v0, 1, v165
	ds_read2_b32 v[86:87], v90 offset0:32 offset1:64
	ds_read2_b32 v[88:89], v90 offset0:96 offset1:128
	ds_read2_b32 v[90:91], v90 offset0:160 offset1:192
	s_waitcnt lgkmcnt(2)
	v_add_f32_e32 v86, 0, v86
	s_waitcnt lgkmcnt(1)
	v_add_f32_e32 v86, v86, v88
	v_add_u32_e32 v88, 0x2200, v100
	ds_read2_b32 v[92:93], v88 offset0:96 offset1:128
	v_add_u32_e32 v88, 0x2400, v100
	ds_read2_b32 v[94:95], v88 offset0:32 offset1:64
	ds_read2_b32 v[96:97], v88 offset0:96 offset1:128
	ds_read2_b32 v[98:99], v88 offset0:160 offset1:192
	v_add_u32_e32 v88, 0x2600, v100
	s_waitcnt lgkmcnt(4)
	v_add_f32_e32 v86, v86, v90
	ds_read2_b32 v[100:101], v88 offset0:96 offset1:128
	s_waitcnt lgkmcnt(4)
	v_add_f32_e32 v86, v86, v92
	s_waitcnt lgkmcnt(3)
	v_add_f32_e32 v86, v86, v94
	s_waitcnt lgkmcnt(2)
	v_add_f32_e32 v86, v86, v96
	s_waitcnt lgkmcnt(1)
	v_add_f32_e32 v86, v86, v98
	s_waitcnt lgkmcnt(0)
	v_add_f32_e32 v86, v86, v100
	v_fmamk_f32 v86, v86, 0x3b000000, v180
	v_cmp_gt_f32_e32 vcc, s19, v86
	v_mul_f32_e32 v88, 0x4f800000, v86
	s_nop 0
	v_cndmask_b32_e32 v86, v86, v88, vcc
	v_sqrt_f32_e32 v88, v86
	s_nop 0
	v_add_u32_e32 v90, -1, v88
	v_fma_f32 v92, -v90, v88, v86
	v_cmp_ge_f32_e64 s[40:41], 0, v92
	v_add_u32_e32 v92, 1, v88
	s_nop 0
	v_cndmask_b32_e64 v90, v88, v90, s[40:41]
	v_fma_f32 v88, -v92, v88, v86
	v_cmp_lt_f32_e64 s[40:41], 0, v88
	s_nop 1
	v_cndmask_b32_e64 v88, v90, v92, s[40:41]
	v_mul_f32_e32 v90, 0x37800000, v88
	v_cndmask_b32_e32 v88, v88, v90, vcc
	v_cmp_class_f32_e32 vcc, v86, v181
	s_nop 1
	v_cndmask_b32_e32 v86, v88, v86, vcc
	v_div_scale_f32 v88, s[4:5], v86, v86, 1.0
	v_rcp_f32_e32 v90, v88
	s_nop 0
	v_fma_f32 v92, -v88, v90, 1.0
	v_fmac_f32_e32 v90, v92, v90
	v_div_scale_f32 v92, vcc, 1.0, v86, 1.0
	v_mul_f32_e32 v94, v92, v90
	v_fma_f32 v96, -v88, v94, v92
	v_fmac_f32_e32 v94, v96, v90
	v_fma_f32 v88, -v88, v94, v92
	v_div_fmas_f32 v88, v88, v90, v94
	v_div_fixup_f32 v86, v88, v86, 1.0
	v_pk_mul_f32 v[110:111], v[110:111], v[86:87] op_sel_hi:[1,0]
	v_pk_mul_f32 v[66:67], v[66:67], v[86:87] op_sel_hi:[1,0]
	s_waitcnt vmcnt(0)
	v_pk_mul_f32 v[110:111], v[30:31], v[110:111]
	v_pk_mul_f32 v[68:69], v[68:69], v[86:87] op_sel_hi:[1,0]
	v_cvt_pk_bf16_f32 v116, v110, v111
	v_pk_mul_f32 v[110:111], v[112:113], v[86:87] op_sel_hi:[1,0]
	v_pk_mul_f32 v[66:67], v[2:3], v[66:67]
	v_pk_mul_f32 v[110:111], v[32:33], v[110:111]
	v_pk_mul_f32 v[68:69], v[4:5], v[68:69]
	v_cvt_pk_bf16_f32 v117, v110, v111
	v_lshl_add_u64 v[110:111], v[114:115], 0, v[0:1]
	v_cvt_pk_bf16_f32 v66, v66, v67
	v_cvt_pk_bf16_f32 v67, v68, v69
	global_store_dwordx2 v[110:111], v[66:67], off offset:112
	v_add_f32_e32 v66, 0, v87
	v_add_f32_e32 v66, v66, v89
	v_add_f32_e32 v66, v66, v91
	v_add_f32_e32 v66, v66, v93
	v_add_f32_e32 v66, v66, v95
	v_add_f32_e32 v66, v66, v97
	v_add_f32_e32 v66, v66, v99
	v_add_f32_e32 v66, v66, v101
	v_fmamk_f32 v66, v66, 0x3b000000, v180
	v_cmp_gt_f32_e32 vcc, s19, v66
	v_mul_f32_e32 v67, 0x4f800000, v66
	v_pk_mul_f32 v[72:73], v[72:73], v[86:87] op_sel_hi:[1,0]
	v_cndmask_b32_e32 v66, v66, v67, vcc
	v_sqrt_f32_e32 v67, v66
	v_pk_mul_f32 v[70:71], v[70:71], v[86:87] op_sel_hi:[1,0]
	v_pk_mul_f32 v[72:73], v[6:7], v[72:73]
	v_pk_mul_f32 v[70:71], v[8:9], v[70:71]
	v_add_u32_e32 v68, -1, v67
	v_fma_f32 v69, -v68, v67, v66
	v_cmp_ge_f32_e64 s[40:41], 0, v69
	v_add_u32_e32 v69, 1, v67
	v_cvt_pk_bf16_f32 v72, v72, v73
	v_cndmask_b32_e64 v68, v67, v68, s[40:41]
	v_fma_f32 v67, -v69, v67, v66
	v_cmp_lt_f32_e64 s[40:41], 0, v67
	v_cvt_pk_bf16_f32 v73, v70, v71
	v_pk_mul_f32 v[108:109], v[108:109], v[86:87] op_sel_hi:[1,0]
	v_cndmask_b32_e64 v67, v68, v69, s[40:41]
	v_mul_f32_e32 v68, 0x37800000, v67
	v_cndmask_b32_e32 v67, v67, v68, vcc
	v_cmp_class_f32_e32 vcc, v66, v181
	v_pk_mul_f32 v[108:109], v[26:27], v[108:109]
	v_pk_mul_f32 v[106:107], v[106:107], v[86:87] op_sel_hi:[1,0]
	v_cndmask_b32_e32 v66, v67, v66, vcc
	v_div_scale_f32 v67, s[4:5], v66, v66, 1.0
	v_rcp_f32_e32 v68, v67
	v_pk_mul_f32 v[106:107], v[28:29], v[106:107]
	v_pk_mul_f32 v[104:105], v[104:105], v[86:87] op_sel_hi:[1,0]
	v_pk_mul_f32 v[102:103], v[102:103], v[86:87] op_sel_hi:[1,0]
	v_fma_f32 v69, -v67, v68, 1.0
	v_fmac_f32_e32 v68, v69, v68
	v_div_scale_f32 v69, vcc, 1.0, v66, 1.0
	v_mul_f32_e32 v70, v69, v68
	v_fma_f32 v71, -v67, v70, v69
	v_fmac_f32_e32 v70, v71, v68
	v_fma_f32 v67, -v67, v70, v69
	v_div_fmas_f32 v67, v67, v68, v70
	v_div_fixup_f32 v66, v67, v66, 1.0
	v_pk_mul_f32 v[62:63], v[62:63], v[66:67] op_sel_hi:[1,0]
	v_lshlrev_b64 v[68:69], 11, v[162:163]
	v_pk_mul_f32 v[30:31], v[30:31], v[62:63]
	v_pk_mul_f32 v[62:63], v[64:65], v[66:67] op_sel_hi:[1,0]
	v_lshl_add_u64 v[68:69], s[2:3], 0, v[68:69]
	v_pk_mul_f32 v[32:33], v[32:33], v[62:63]
	v_cvt_pk_bf16_f32 v30, v30, v31
	v_cvt_pk_bf16_f32 v31, v32, v33
	v_lshl_add_u64 v[118:119], v[68:69], 0, v[0:1]
	global_store_dwordx2 v[118:119], v[30:31], off
	v_pk_mul_f32 v[30:31], v[56:57], v[66:67] op_sel_hi:[1,0]
	v_pk_mul_f32 v[104:105], v[22:23], v[104:105]
	v_pk_mul_f32 v[26:27], v[26:27], v[30:31]
	v_pk_mul_f32 v[30:31], v[60:61], v[66:67] op_sel_hi:[1,0]
	v_cvt_pk_bf16_f32 v26, v26, v27
	v_pk_mul_f32 v[28:29], v[28:29], v[30:31]
	v_pk_mul_f32 v[102:103], v[24:25], v[102:103]
	v_cvt_pk_bf16_f32 v27, v28, v29
	global_store_dwordx2 v[118:119], v[26:27], off offset:16
	v_pk_mul_f32 v[26:27], v[52:53], v[66:67] op_sel_hi:[1,0]
	v_pk_mul_f32 v[84:85], v[84:85], v[86:87] op_sel_hi:[1,0]
	v_pk_mul_f32 v[22:23], v[22:23], v[26:27]
	v_pk_mul_f32 v[26:27], v[58:59], v[66:67] op_sel_hi:[1,0]
	v_cvt_pk_bf16_f32 v22, v22, v23
	v_pk_mul_f32 v[24:25], v[24:25], v[26:27]
	v_pk_mul_f32 v[84:85], v[18:19], v[84:85]
	v_cvt_pk_bf16_f32 v23, v24, v25
	global_store_dwordx2 v[118:119], v[22:23], off offset:32
	v_pk_mul_f32 v[22:23], v[50:51], v[66:67] op_sel_hi:[1,0]
	v_pk_mul_f32 v[82:83], v[82:83], v[86:87] op_sel_hi:[1,0]
	v_pk_mul_f32 v[18:19], v[18:19], v[22:23]
	v_pk_mul_f32 v[22:23], v[54:55], v[66:67] op_sel_hi:[1,0]
	v_pk_mul_f32 v[82:83], v[20:21], v[82:83]
	v_pk_mul_f32 v[20:21], v[20:21], v[22:23]
	v_cvt_pk_bf16_f32 v18, v18, v19
	v_cvt_pk_bf16_f32 v19, v20, v21
	v_pk_mul_f32 v[80:81], v[80:81], v[86:87] op_sel_hi:[1,0]
	global_store_dwordx2 v[118:119], v[18:19], off offset:48
	v_pk_mul_f32 v[18:19], v[44:45], v[66:67] op_sel_hi:[1,0]
	v_pk_mul_f32 v[80:81], v[14:15], v[80:81]
	v_pk_mul_f32 v[78:79], v[78:79], v[86:87] op_sel_hi:[1,0]
	v_pk_mul_f32 v[14:15], v[14:15], v[18:19]
	v_pk_mul_f32 v[18:19], v[48:49], v[66:67] op_sel_hi:[1,0]
	v_pk_mul_f32 v[78:79], v[16:17], v[78:79]
	v_pk_mul_f32 v[16:17], v[16:17], v[18:19]
	v_cvt_pk_bf16_f32 v14, v14, v15
	v_cvt_pk_bf16_f32 v15, v16, v17
	v_pk_mul_f32 v[76:77], v[76:77], v[86:87] op_sel_hi:[1,0]
	global_store_dwordx2 v[118:119], v[14:15], off offset:64
	v_pk_mul_f32 v[14:15], v[40:41], v[66:67] op_sel_hi:[1,0]
	v_pk_mul_f32 v[76:77], v[10:11], v[76:77]
	v_pk_mul_f32 v[74:75], v[74:75], v[86:87] op_sel_hi:[1,0]
	v_pk_mul_f32 v[10:11], v[10:11], v[14:15]
	v_pk_mul_f32 v[14:15], v[46:47], v[66:67] op_sel_hi:[1,0]
	v_pk_mul_f32 v[74:75], v[12:13], v[74:75]
	v_pk_mul_f32 v[12:13], v[12:13], v[14:15]
	v_cvt_pk_bf16_f32 v10, v10, v11
	v_cvt_pk_bf16_f32 v11, v12, v13
	global_store_dwordx2 v[118:119], v[10:11], off offset:80
	v_pk_mul_f32 v[10:11], v[38:39], v[66:67] op_sel_hi:[1,0]
	v_cvt_pk_bf16_f32 v108, v108, v109
	v_pk_mul_f32 v[6:7], v[6:7], v[10:11]
	v_pk_mul_f32 v[10:11], v[42:43], v[66:67] op_sel_hi:[1,0]
	v_cvt_pk_bf16_f32 v6, v6, v7
	v_pk_mul_f32 v[8:9], v[8:9], v[10:11]
	v_cvt_pk_bf16_f32 v109, v106, v107
	v_cvt_pk_bf16_f32 v7, v8, v9
	global_store_dwordx2 v[118:119], v[6:7], off offset:96
	v_pk_mul_f32 v[6:7], v[36:37], v[66:67] op_sel_hi:[1,0]
	v_cvt_pk_bf16_f32 v104, v104, v105
	v_pk_mul_f32 v[2:3], v[2:3], v[6:7]
	v_cvt_pk_bf16_f32 v105, v102, v103
	v_cvt_pk_bf16_f32 v84, v84, v85
	v_cvt_pk_bf16_f32 v85, v82, v83
	v_cvt_pk_bf16_f32 v80, v80, v81
	v_cvt_pk_bf16_f32 v81, v78, v79
	v_cvt_pk_bf16_f32 v76, v76, v77
	v_cvt_pk_bf16_f32 v77, v74, v75
	v_cvt_pk_bf16_f32 v120, v2, v3
	v_pk_mul_f32 v[2:3], v[34:35], v[66:67] op_sel_hi:[1,0]
	global_store_dwordx2 v[110:111], v[116:117], off
	global_store_dwordx2 v[110:111], v[108:109], off offset:16
	global_store_dwordx2 v[110:111], v[104:105], off offset:32
	global_store_dwordx2 v[110:111], v[84:85], off offset:48
	global_store_dwordx2 v[110:111], v[80:81], off offset:64
	global_store_dwordx2 v[110:111], v[76:77], off offset:80
	global_store_dwordx2 v[110:111], v[72:73], off offset:96
	v_pk_mul_f32 v[122:123], v[4:5], v[2:3]
	s_cbranch_execnz .LBB0_1017
